# FFN-in GEMM loop: second-group B fragments read last, waited after first MFMA group (lgkmcnt(4) at barrier)
# speedup vs baseline: 1.0082x; 1.0045x over previous
; #define PG8_STAGE(bufoff, gbase, voff) do { _Pragma("unroll") for (int _i = 0; _i < 2; ++_i) \
;         __builtin_amdgcn_global_load_lds((const unsigned*)((const char*)(gbase) + (voff)[_i]), (LAS unsigned*)(lds + (bufoff) + ldsw + _i * 8192), 16, 0, 0); } while (0)
; #define PG8_LDA(dst, b, h) do { _Pragma("unroll") for (int m = 0; m < 4; ++m) _Pragma("unroll") for (int k = 0; k < 2; ++k) dst[m][k] = *(const LAS bf16x8*)(lds + PG8_SA(b, h) + aoff + m * 2048 + k * 1024); } while (0)
; #define PG8_LDB(dst, b, h) do { _Pragma("unroll") for (int n = 0; n < 2; ++n) _Pragma("unroll") for (int k = 0; k < 2; ++k) dst[n][k] = *(const LAS bf16x8*)(lds + PG8_SB(b, h) + boff + n * 2048 + k * 1024); } while (0)
; #define PG8_MMA(ai, bj, At, Bt) do { __builtin_amdgcn_s_setprio(1); _Pragma("unroll") for (int m = 0; m < 4; ++m) _Pragma("unroll") for (int n = 0; n < 2; ++n) _Pragma("unroll") for (int k = 0; k < 2; ++k) \
;         acc[ai][bj][m][n] = __builtin_amdgcn_mfma_f32_16x16x32_bf16(Bt[n][k], At[m][k], acc[ai][bj][m][n], 0, 0, 0); __builtin_amdgcn_s_setprio(0); } while (0)
; #define PG8_WAIT_V(n) asm volatile("s_waitcnt vmcnt(" #n ")" ::: "memory")
; #define PG8_WAIT_L(n) asm volatile("s_waitcnt lgkmcnt(" #n ")" ::: "memory")
; #define PG8_BAR __builtin_amdgcn_s_barrier()
; #define PG8_SCHED __builtin_amdgcn_sched_barrier(0)
; template <class Epi>
; __device__ __forceinline__ void gemm_phase(LAS unsigned char* lds, const Gemm g, const StaticOrder& S, const Epi& E, const int tid_in) {
;     ...
;             PG8_LDB(B0, 0, 0); PG8_LDB(B1, 0, 1); PG8_SCHED; PG8_LDA(At, 0, 0); PG8_STAGE(PG8_SA(1, 1), a1 + hstepA, voffA);
;             PG8_WAIT_V(8); PG8_WAIT_L(0); PG8_BAR; PG8_MMA(0, 0, At, B0); PG8_MMA(0, 1, At, B1); PG8_BAR; PG8_SCHED;
.LBB0_232:
	s_add_u32 s20, s36, 0xfffc0080
	s_addc_u32 s21, s37, -1
	s_add_i32 s57, 0, 0x10000
	s_cmp_eq_u32 s56, 12
	s_cselect_b32 s21, s7, s21
	s_cselect_b32 s20, s17, s20
	s_cselect_b32 s35, s48, s39
	s_cselect_b32 s34, s50, s38
	s_add_i32 s58, 0, 0x14000
	v_add_u32_e32 v44, s57, v163
	v_add_u32_e32 v160, s58, v163
	ds_read_b128 v[32:35], v44
	ds_read_b128 v[36:39], v44 offset:1024
	ds_read_b128 v[40:43], v44 offset:2048
	ds_read_b128 v[44:47], v44 offset:3072
	ds_read_b128 v[184:187], v167
	ds_read_b128 v[188:191], v167 offset:1024
	ds_read_b128 v[192:195], v167 offset:2048
	ds_read_b128 v[196:199], v167 offset:3072
	ds_read_b128 v[200:203], v167 offset:4096
	ds_read_b128 v[204:207], v167 offset:5120
	ds_read_b128 v[208:211], v167 offset:6144
	ds_read_b128 v[212:215], v167 offset:7168
	ds_read_b128 v[168:171], v160
	ds_read_b128 v[172:175], v160 offset:1024
	ds_read_b128 v[176:179], v160 offset:2048
	ds_read_b128 v[180:183], v160 offset:3072
	v_lshl_add_u64 v[160:161], s[36:37], 0, v[156:157]
	s_add_i32 m0, s46, 0xc000
	s_nop 0
	global_load_lds_dwordx4 v[160:161], off
	v_lshl_add_u64 v[160:161], s[36:37], 0, v[158:159]
	s_add_i32 m0, s46, 0xe000
	s_nop 0
	global_load_lds_dwordx4 v[160:161], off
	s_waitcnt vmcnt(8)
	s_waitcnt lgkmcnt(4)
	s_barrier
	s_setprio 1
	s_waitcnt lgkmcnt(4)
	v_mfma_f32_16x16x32_bf16 v[142:145], v[32:35], v[184:187], v[142:145]
	v_mfma_f32_16x16x32_bf16 v[138:141], v[40:43], v[184:187], v[138:141]
	v_mfma_f32_16x16x32_bf16 v[124:127], v[32:35], v[192:195], v[124:127]
	v_mfma_f32_16x16x32_bf16 v[120:123], v[40:43], v[192:195], v[120:123]
	v_mfma_f32_16x16x32_bf16 v[108:111], v[32:35], v[200:203], v[108:111]
	v_mfma_f32_16x16x32_bf16 v[104:107], v[40:43], v[200:203], v[104:107]
	v_mfma_f32_16x16x32_bf16 v[92:95], v[32:35], v[208:211], v[92:95]
	v_mfma_f32_16x16x32_bf16 v[88:91], v[40:43], v[208:211], v[88:91]
	v_mfma_f32_16x16x32_bf16 v[142:145], v[36:39], v[188:191], v[142:145]
	v_mfma_f32_16x16x32_bf16 v[138:141], v[44:47], v[188:191], v[138:141]
	v_mfma_f32_16x16x32_bf16 v[124:127], v[36:39], v[196:199], v[124:127]
	v_mfma_f32_16x16x32_bf16 v[120:123], v[44:47], v[196:199], v[120:123]
	v_mfma_f32_16x16x32_bf16 v[108:111], v[36:39], v[204:207], v[108:111]
	v_mfma_f32_16x16x32_bf16 v[104:107], v[44:47], v[204:207], v[104:107]
	v_mfma_f32_16x16x32_bf16 v[92:95], v[36:39], v[212:215], v[92:95]
	v_mfma_f32_16x16x32_bf16 v[88:91], v[44:47], v[212:215], v[88:91]
	s_setprio 0
	s_setprio 1
	s_waitcnt lgkmcnt(0)
	v_mfma_f32_16x16x32_bf16 v[134:137], v[168:171], v[184:187], v[134:137]
	v_mfma_f32_16x16x32_bf16 v[130:133], v[176:179], v[184:187], v[130:133]
	v_mfma_f32_16x16x32_bf16 v[116:119], v[168:171], v[192:195], v[116:119]
	v_mfma_f32_16x16x32_bf16 v[112:115], v[176:179], v[192:195], v[112:115]
	v_mfma_f32_16x16x32_bf16 v[100:103], v[168:171], v[200:203], v[100:103]
	v_mfma_f32_16x16x32_bf16 v[96:99], v[176:179], v[200:203], v[96:99]
	v_mfma_f32_16x16x32_bf16 v[84:87], v[168:171], v[208:211], v[84:87]
	v_mfma_f32_16x16x32_bf16 v[80:83], v[176:179], v[208:211], v[80:83]
	v_mfma_f32_16x16x32_bf16 v[134:137], v[172:175], v[188:191], v[134:137]
	v_mfma_f32_16x16x32_bf16 v[130:133], v[180:183], v[188:191], v[130:133]
	v_mfma_f32_16x16x32_bf16 v[116:119], v[172:175], v[196:199], v[116:119]
	v_mfma_f32_16x16x32_bf16 v[112:115], v[180:183], v[196:199], v[112:115]
	v_mfma_f32_16x16x32_bf16 v[100:103], v[172:175], v[204:207], v[100:103]
	v_mfma_f32_16x16x32_bf16 v[96:99], v[180:183], v[204:207], v[96:99]
	v_mfma_f32_16x16x32_bf16 v[84:87], v[172:175], v[212:215], v[84:87]
	v_mfma_f32_16x16x32_bf16 v[80:83], v[180:183], v[212:215], v[80:83]
	s_setprio 0
	s_barrier
	s_add_i32 s57, s57, s45
	v_lshl_add_u64 v[160:161], s[34:35], 0, v[148:149]
	s_mov_b32 m0, s57
	ds_read_b128 v[184:187], v167 offset:16384
	ds_read_b128 v[188:191], v167 offset:17408
	ds_read_b128 v[192:195], v167 offset:18432
	ds_read_b128 v[196:199], v167 offset:19456
	ds_read_b128 v[200:203], v167 offset:20480
	ds_read_b128 v[204:207], v167 offset:21504
	ds_read_b128 v[208:211], v167 offset:22528
	ds_read_b128 v[212:215], v167 offset:23552
	global_load_lds_dwordx4 v[160:161], off
	s_add_i32 m0, s57, 0x2000
	s_add_u32 s60, s34, 0x40000
	v_lshl_add_u64 v[216:217], s[34:35], 0, v[152:153]
	s_addc_u32 s61, s35, 0
	s_add_i32 s57, s58, s45
	global_load_lds_dwordx4 v[216:217], off
	v_lshl_add_u64 v[218:219], s[60:61], 0, v[148:149]
	s_mov_b32 m0, s57
	v_lshl_add_u64 v[220:221], s[20:21], 0, v[150:151]
	global_load_lds_dwordx4 v[218:219], off
	v_lshl_add_u64 v[218:219], s[60:61], 0, v[152:153]
	s_add_i32 m0, s57, 0x2000
	s_nop 0
	global_load_lds_dwordx4 v[218:219], off
	v_lshl_add_u64 v[218:219], s[20:21], 0, v[146:147]
	s_mov_b32 m0, s46
	s_nop 0
	global_load_lds_dwordx4 v[218:219], off
	s_mov_b32 m0, s47
	s_nop 0
	global_load_lds_dwordx4 v[220:221], off
	s_waitcnt vmcnt(8)
	s_waitcnt lgkmcnt(0)
	s_barrier
; #define PG8_STAGE(bufoff, gbase, voff) do { _Pragma("unroll") for (int _i = 0; _i < 2; ++_i) \
;         __builtin_amdgcn_global_load_lds((const unsigned*)((const char*)(gbase) + (voff)[_i]), (LAS unsigned*)(lds + (bufoff) + ldsw + _i * 8192), 16, 0, 0); } while (0)
; #define PG8_LDA(dst, b, h) do { _Pragma("unroll") for (int m = 0; m < 4; ++m) _Pragma("unroll") for (int k = 0; k < 2; ++k) dst[m][k] = *(const LAS bf16x8*)(lds + PG8_SA(b, h) + aoff + m * 2048 + k * 1024); } while (0)
; #define PG8_LDB(dst, b, h) do { _Pragma("unroll") for (int n = 0; n < 2; ++n) _Pragma("unroll") for (int k = 0; k < 2; ++k) dst[n][k] = *(const LAS bf16x8*)(lds + PG8_SB(b, h) + boff + n * 2048 + k * 1024); } while (0)
; #define PG8_MMA(ai, bj, At, Bt) do { __builtin_amdgcn_s_setprio(1); _Pragma("unroll") for (int m = 0; m < 4; ++m) _Pragma("unroll") for (int n = 0; n < 2; ++n) _Pragma("unroll") for (int k = 0; k < 2; ++k) \
;         acc[ai][bj][m][n] = __builtin_amdgcn_mfma_f32_16x16x32_bf16(Bt[n][k], At[m][k], acc[ai][bj][m][n], 0, 0, 0); __builtin_amdgcn_s_setprio(0); } while (0)
; #define PG8_WAIT_V(n) asm volatile("s_waitcnt vmcnt(" #n ")" ::: "memory")
; #define PG8_WAIT_L(n) asm volatile("s_waitcnt lgkmcnt(" #n ")" ::: "memory")
; #define PG8_BAR __builtin_amdgcn_s_barrier()
; #define PG8_SCHED __builtin_amdgcn_sched_barrier(0)
; template <class Epi>
; __device__ __forceinline__ void gemm_phase(LAS unsigned char* lds, const Gemm g, const StaticOrder& S, const Epi& E, const int tid_in) {
;     ...
;             PG8_WAIT_V(8); PG8_WAIT_L(0); PG8_BAR; PG8_MMA(1, 0, At, B0); PG8_MMA(1, 1, At, B1); PG8_BAR; PG8_SCHED;
;             PG8_LDB(B0, 1, 0); PG8_LDB(B1, 1, 1); PG8_SCHED; PG8_LDA(At, 1, 0); PG8_STAGE(PG8_SA(0, 1), a2 + hstepA, voffA);
;             PG8_WAIT_V(8); PG8_WAIT_L(0); PG8_BAR; PG8_MMA(0, 0, At, B0); PG8_MMA(0, 1, At, B1); PG8_BAR; PG8_SCHED;
	s_setprio 1
	s_waitcnt lgkmcnt(0)
	v_mfma_f32_16x16x32_bf16 v[76:79], v[32:35], v[184:187], v[76:79]
	v_mfma_f32_16x16x32_bf16 v[72:75], v[40:43], v[184:187], v[72:75]
	v_mfma_f32_16x16x32_bf16 v[60:63], v[32:35], v[192:195], v[60:63]
	v_mfma_f32_16x16x32_bf16 v[56:59], v[40:43], v[192:195], v[56:59]
	v_mfma_f32_16x16x32_bf16 v[28:31], v[32:35], v[200:203], v[28:31]
	v_mfma_f32_16x16x32_bf16 v[24:27], v[40:43], v[200:203], v[24:27]
	v_mfma_f32_16x16x32_bf16 v[12:15], v[32:35], v[208:211], v[12:15]
	v_mfma_f32_16x16x32_bf16 v[8:11], v[40:43], v[208:211], v[8:11]
	v_mfma_f32_16x16x32_bf16 v[76:79], v[36:39], v[188:191], v[76:79]
	v_mfma_f32_16x16x32_bf16 v[72:75], v[44:47], v[188:191], v[72:75]
	v_mfma_f32_16x16x32_bf16 v[60:63], v[36:39], v[196:199], v[60:63]
	v_mfma_f32_16x16x32_bf16 v[56:59], v[44:47], v[196:199], v[56:59]
	v_mfma_f32_16x16x32_bf16 v[28:31], v[36:39], v[204:207], v[28:31]
	v_mfma_f32_16x16x32_bf16 v[24:27], v[44:47], v[204:207], v[24:27]
	v_mfma_f32_16x16x32_bf16 v[12:15], v[36:39], v[212:215], v[12:15]
	v_mfma_f32_16x16x32_bf16 v[8:11], v[44:47], v[212:215], v[8:11]
	s_setprio 0
	s_setprio 1
	v_mfma_f32_16x16x32_bf16 v[20:23], v[168:171], v[200:203], v[20:23]
	v_mfma_f32_16x16x32_bf16 v[16:19], v[176:179], v[200:203], v[16:19]
	v_mfma_f32_16x16x32_bf16 v[4:7], v[168:171], v[208:211], v[4:7]
	v_mfma_f32_16x16x32_bf16 v[0:3], v[176:179], v[208:211], v[0:3]
	v_mfma_f32_16x16x32_bf16 v[32:35], v[168:171], v[184:187], v[68:71]
	v_mfma_f32_16x16x32_bf16 v[36:39], v[176:179], v[184:187], v[64:67]
	v_mfma_f32_16x16x32_bf16 v[40:43], v[168:171], v[192:195], v[52:55]
	v_mfma_f32_16x16x32_bf16 v[44:47], v[176:179], v[192:195], v[48:51]
	v_mfma_f32_16x16x32_bf16 v[20:23], v[172:175], v[204:207], v[20:23]
	v_mfma_f32_16x16x32_bf16 v[16:19], v[180:183], v[204:207], v[16:19]
	v_mfma_f32_16x16x32_bf16 v[4:7], v[172:175], v[212:215], v[4:7]
	v_mfma_f32_16x16x32_bf16 v[0:3], v[180:183], v[212:215], v[0:3]
	v_mfma_f32_16x16x32_bf16 v[32:35], v[172:175], v[188:191], v[32:35]
	v_mfma_f32_16x16x32_bf16 v[36:39], v[180:183], v[188:191], v[36:39]
	v_mfma_f32_16x16x32_bf16 v[40:43], v[172:175], v[196:199], v[40:43]
	v_mfma_f32_16x16x32_bf16 v[44:47], v[180:183], v[196:199], v[44:47]
	s_setprio 0
	s_barrier
	s_add_i32 s57, 0, 0x18000
	s_add_i32 s58, 0, 0x1c000
	v_add_u32_e32 v68, s57, v163
	v_add_u32_e32 v180, s58, v163
	ds_read_b128 v[48:51], v68
	ds_read_b128 v[52:55], v68 offset:1024
	ds_read_b128 v[64:67], v68 offset:2048
	ds_read_b128 v[68:71], v68 offset:3072
	ds_read_b128 v[184:187], v167 offset:32768
	ds_read_b128 v[188:191], v167 offset:33792
	ds_read_b128 v[192:195], v167 offset:34816
	ds_read_b128 v[196:199], v167 offset:35840
	ds_read_b128 v[200:203], v167 offset:36864
	ds_read_b128 v[204:207], v167 offset:37888
	ds_read_b128 v[208:211], v167 offset:38912
	ds_read_b128 v[212:215], v167 offset:39936
	ds_read_b128 v[168:171], v180
	ds_read_b128 v[172:175], v180 offset:1024
	ds_read_b128 v[176:179], v180 offset:2048
	ds_read_b128 v[180:183], v180 offset:3072
	s_add_u32 s20, s20, 0x40000
	s_addc_u32 s21, s21, 0
	s_mov_b32 m0, s71
	v_lshl_add_u64 v[222:223], s[20:21], 0, v[146:147]
	global_load_lds_dwordx4 v[222:223], off
	v_lshl_add_u64 v[222:223], s[20:21], 0, v[150:151]
	s_mov_b32 m0, s86
	s_nop 0
	global_load_lds_dwordx4 v[222:223], off
	s_waitcnt vmcnt(8)
	s_waitcnt lgkmcnt(4)
	s_barrier
	s_setprio 1
	s_waitcnt lgkmcnt(4)
	v_mfma_f32_16x16x32_bf16 v[142:145], v[48:51], v[184:187], v[142:145]
	v_mfma_f32_16x16x32_bf16 v[138:141], v[64:67], v[184:187], v[138:141]
	v_mfma_f32_16x16x32_bf16 v[124:127], v[48:51], v[192:195], v[124:127]
	v_mfma_f32_16x16x32_bf16 v[120:123], v[64:67], v[192:195], v[120:123]
	v_mfma_f32_16x16x32_bf16 v[108:111], v[48:51], v[200:203], v[108:111]
	v_mfma_f32_16x16x32_bf16 v[104:107], v[64:67], v[200:203], v[104:107]
	v_mfma_f32_16x16x32_bf16 v[92:95], v[48:51], v[208:211], v[92:95]
	v_mfma_f32_16x16x32_bf16 v[88:91], v[64:67], v[208:211], v[88:91]
	v_mfma_f32_16x16x32_bf16 v[142:145], v[52:55], v[188:191], v[142:145]
	v_mfma_f32_16x16x32_bf16 v[138:141], v[68:71], v[188:191], v[138:141]
	v_mfma_f32_16x16x32_bf16 v[124:127], v[52:55], v[196:199], v[124:127]
	v_mfma_f32_16x16x32_bf16 v[120:123], v[68:71], v[196:199], v[120:123]
	v_mfma_f32_16x16x32_bf16 v[108:111], v[52:55], v[204:207], v[108:111]
	v_mfma_f32_16x16x32_bf16 v[104:107], v[68:71], v[204:207], v[104:107]
	v_mfma_f32_16x16x32_bf16 v[92:95], v[52:55], v[212:215], v[92:95]
	v_mfma_f32_16x16x32_bf16 v[88:91], v[68:71], v[212:215], v[88:91]
	s_setprio 0
	s_setprio 1
	s_waitcnt lgkmcnt(0)
	v_mfma_f32_16x16x32_bf16 v[134:137], v[168:171], v[184:187], v[134:137]
	v_mfma_f32_16x16x32_bf16 v[130:133], v[176:179], v[184:187], v[130:133]
	v_mfma_f32_16x16x32_bf16 v[116:119], v[168:171], v[192:195], v[116:119]
	v_mfma_f32_16x16x32_bf16 v[112:115], v[176:179], v[192:195], v[112:115]
	v_mfma_f32_16x16x32_bf16 v[100:103], v[168:171], v[200:203], v[100:103]
	v_mfma_f32_16x16x32_bf16 v[96:99], v[176:179], v[200:203], v[96:99]
	v_mfma_f32_16x16x32_bf16 v[84:87], v[168:171], v[208:211], v[84:87]
	v_mfma_f32_16x16x32_bf16 v[80:83], v[176:179], v[208:211], v[80:83]
	v_mfma_f32_16x16x32_bf16 v[134:137], v[172:175], v[188:191], v[134:137]
	v_mfma_f32_16x16x32_bf16 v[130:133], v[180:183], v[188:191], v[130:133]
	v_mfma_f32_16x16x32_bf16 v[116:119], v[172:175], v[196:199], v[116:119]
	v_mfma_f32_16x16x32_bf16 v[112:115], v[180:183], v[196:199], v[112:115]
	v_mfma_f32_16x16x32_bf16 v[100:103], v[172:175], v[204:207], v[100:103]
	v_mfma_f32_16x16x32_bf16 v[96:99], v[180:183], v[204:207], v[96:99]
	v_mfma_f32_16x16x32_bf16 v[84:87], v[172:175], v[212:215], v[84:87]
	v_mfma_f32_16x16x32_bf16 v[80:83], v[180:183], v[212:215], v[80:83]
	s_setprio 0
	s_barrier
; #define PG8_STAGE(bufoff, gbase, voff) do { _Pragma("unroll") for (int _i = 0; _i < 2; ++_i) \
;         __builtin_amdgcn_global_load_lds((const unsigned*)((const char*)(gbase) + (voff)[_i]), (LAS unsigned*)(lds + (bufoff) + ldsw + _i * 8192), 16, 0, 0); } while (0)
; #define PG8_LDA(dst, b, h) do { _Pragma("unroll") for (int m = 0; m < 4; ++m) _Pragma("unroll") for (int k = 0; k < 2; ++k) dst[m][k] = *(const LAS bf16x8*)(lds + PG8_SA(b, h) + aoff + m * 2048 + k * 1024); } while (0)
; #define PG8_MMA(ai, bj, At, Bt) do { __builtin_amdgcn_s_setprio(1); _Pragma("unroll") for (int m = 0; m < 4; ++m) _Pragma("unroll") for (int n = 0; n < 2; ++n) _Pragma("unroll") for (int k = 0; k < 2; ++k) \
;         acc[ai][bj][m][n] = __builtin_amdgcn_mfma_f32_16x16x32_bf16(Bt[n][k], At[m][k], acc[ai][bj][m][n], 0, 0, 0); __builtin_amdgcn_s_setprio(0); } while (0)
; #define PG8_WAIT_V(n) asm volatile("s_waitcnt vmcnt(" #n ")" ::: "memory")
; #define PG8_WAIT_L(n) asm volatile("s_waitcnt lgkmcnt(" #n ")" ::: "memory")
; #define PG8_BAR __builtin_amdgcn_s_barrier()
; #define PG8_SCHED __builtin_amdgcn_sched_barrier(0)
; template <class Epi>
; __device__ __forceinline__ void gemm_phase(LAS unsigned char* lds, const Gemm g, const StaticOrder& S, const Epi& E, const int tid_in) {
;     ...
;             PG8_LDA(At, 1, 1); PG8_STAGE(PG8_SB(1, 0), b3, voffB); PG8_STAGE(PG8_SB(1, 1), b3 + hstepB, voffB); PG8_STAGE(PG8_SA(1, 0), a3, voffA);
;             PG8_WAIT_V(8); PG8_WAIT_L(0); PG8_BAR; PG8_MMA(1, 0, At, B0); PG8_MMA(1, 1, At, B1); PG8_BAR; PG8_SCHED;
;         }
	s_add_i32 s20, s57, s45
	v_lshl_add_u64 v[160:161], v[160:161], 0, s[54:55]
	s_mov_b32 m0, s20
	ds_read_b128 v[184:187], v167 offset:49152
	ds_read_b128 v[188:191], v167 offset:50176
	ds_read_b128 v[192:195], v167 offset:51200
	ds_read_b128 v[196:199], v167 offset:52224
	ds_read_b128 v[200:203], v167 offset:53248
	ds_read_b128 v[204:207], v167 offset:54272
	ds_read_b128 v[208:211], v167 offset:55296
	ds_read_b128 v[212:215], v167 offset:56320
	global_load_lds_dwordx4 v[160:161], off
	s_add_i32 m0, s20, 0x2000
	s_add_u32 s20, s34, 0x40080
	v_lshl_add_u64 v[160:161], v[216:217], 0, s[54:55]
	s_addc_u32 s21, s35, 0
	s_add_i32 s34, s58, s45
	global_load_lds_dwordx4 v[160:161], off
	v_lshl_add_u64 v[160:161], s[20:21], 0, v[148:149]
	s_mov_b32 m0, s34
	s_nop 0
	global_load_lds_dwordx4 v[160:161], off
	v_lshl_add_u64 v[160:161], s[20:21], 0, v[152:153]
	s_add_i32 m0, s34, 0x2000
	s_nop 0
	global_load_lds_dwordx4 v[160:161], off
	v_lshl_add_u64 v[160:161], v[218:219], 0, s[54:55]
	s_mov_b32 m0, s88
	s_nop 0
	global_load_lds_dwordx4 v[160:161], off
	v_lshl_add_u64 v[160:161], v[220:221], 0, s[54:55]
	s_mov_b32 m0, s89
	s_nop 0
	global_load_lds_dwordx4 v[160:161], off
	s_waitcnt vmcnt(8)
	s_waitcnt lgkmcnt(0)
	s_barrier
	s_setprio 1
	s_waitcnt lgkmcnt(0)
	v_mfma_f32_16x16x32_bf16 v[76:79], v[48:51], v[184:187], v[76:79]
	v_mfma_f32_16x16x32_bf16 v[72:75], v[64:67], v[184:187], v[72:75]
	v_mfma_f32_16x16x32_bf16 v[60:63], v[48:51], v[192:195], v[60:63]
	v_mfma_f32_16x16x32_bf16 v[56:59], v[64:67], v[192:195], v[56:59]
	v_mfma_f32_16x16x32_bf16 v[28:31], v[48:51], v[200:203], v[28:31]
	v_mfma_f32_16x16x32_bf16 v[24:27], v[64:67], v[200:203], v[24:27]
	v_mfma_f32_16x16x32_bf16 v[12:15], v[48:51], v[208:211], v[12:15]
	v_mfma_f32_16x16x32_bf16 v[8:11], v[64:67], v[208:211], v[8:11]
	v_mfma_f32_16x16x32_bf16 v[76:79], v[52:55], v[188:191], v[76:79]
	v_mfma_f32_16x16x32_bf16 v[72:75], v[68:71], v[188:191], v[72:75]
	v_mfma_f32_16x16x32_bf16 v[60:63], v[52:55], v[196:199], v[60:63]
	v_mfma_f32_16x16x32_bf16 v[56:59], v[68:71], v[196:199], v[56:59]
	v_mfma_f32_16x16x32_bf16 v[28:31], v[52:55], v[204:207], v[28:31]
	v_mfma_f32_16x16x32_bf16 v[24:27], v[68:71], v[204:207], v[24:27]
	v_mfma_f32_16x16x32_bf16 v[12:15], v[52:55], v[212:215], v[12:15]
	v_mfma_f32_16x16x32_bf16 v[8:11], v[68:71], v[212:215], v[8:11]
	s_setprio 0
	s_setprio 1
	v_mfma_f32_16x16x32_bf16 v[32:35], v[168:171], v[184:187], v[32:35]
	v_mfma_f32_16x16x32_bf16 v[68:71], v[172:175], v[188:191], v[32:35]
	v_mfma_f32_16x16x32_bf16 v[32:35], v[176:179], v[184:187], v[36:39]
	v_mfma_f32_16x16x32_bf16 v[64:67], v[180:183], v[188:191], v[32:35]
	v_mfma_f32_16x16x32_bf16 v[32:35], v[168:171], v[192:195], v[40:43]
	v_mfma_f32_16x16x32_bf16 v[52:55], v[172:175], v[196:199], v[32:35]
	v_mfma_f32_16x16x32_bf16 v[32:35], v[176:179], v[192:195], v[44:47]
	v_mfma_f32_16x16x32_bf16 v[20:23], v[168:171], v[200:203], v[20:23]
	v_mfma_f32_16x16x32_bf16 v[16:19], v[176:179], v[200:203], v[16:19]
	v_mfma_f32_16x16x32_bf16 v[4:7], v[168:171], v[208:211], v[4:7]
	v_mfma_f32_16x16x32_bf16 v[0:3], v[176:179], v[208:211], v[0:3]
	v_mfma_f32_16x16x32_bf16 v[48:51], v[180:183], v[196:199], v[32:35]
	v_mfma_f32_16x16x32_bf16 v[20:23], v[172:175], v[204:207], v[20:23]
	v_mfma_f32_16x16x32_bf16 v[16:19], v[180:183], v[204:207], v[16:19]
	v_mfma_f32_16x16x32_bf16 v[4:7], v[172:175], v[212:215], v[4:7]
	v_mfma_f32_16x16x32_bf16 v[0:3], v[180:183], v[212:215], v[0:3]
	s_setprio 0
	s_barrier
	s_add_i32 s56, s56, 2
	s_add_u32 s36, s36, 0x100
	s_addc_u32 s37, s37, 0
	s_add_u32 s38, s38, 0x100
	s_addc_u32 s39, s39, 0
	s_cmp_gt_u32 s56, 13
	s_cbranch_scc0 .LBB0_232
	s_and_b64 vcc, exec, s[28:29]
	s_cbranch_vccz .LBB0_235
	s_barrier
